# baseline (speedup 1.0000x reference)
; __device__ __forceinline__ int otid() { int t = threadIdx.x; asm volatile("" : "+v"(t)); return t; }
; __device__ __forceinline__ int obid() { int t = blockIdx.x; asm volatile("" : "+s"(t)); return t; }
; __device__ __forceinline__ void phase_ln(const float* __restrict__ pre, const float* __restrict__ g, const float* __restrict__ bta,
;                          float* __restrict__ outf, u16* __restrict__ outb) {
;   const int tid = otid(), bid = obid();
;   const int w = tid >> 6, l = tid & 63;
;   const int nw = gridDim.x * (blockDim.x >> 6);
;   for (int row = bid * (blockDim.x >> 6) + w; row < NTOK; row += nw) {
;     const f32x4* src = reinterpret_cast<const f32x4*>(pre + (long)row * D);
.LBB0_268:
	v_readlane_b32 s40, v248, 5
	v_readlane_b32 s44, v248, 9
	v_readlane_b32 s45, v248, 10
	s_movk_i32 s27, 0x1000
	s_movk_i32 s34, 0x4000
	s_mov_b64 s[10:11], s[4:5]
	v_readlane_b32 s41, v248, 6
	v_readlane_b32 s42, v248, 7
	v_readlane_b32 s43, v248, 8
	v_readlane_b32 s46, v248, 11
	v_readlane_b32 s47, v248, 12
	v_readlane_b32 s48, v248, 13
	v_readlane_b32 s49, v248, 14
	v_readlane_b32 s50, v248, 15
	v_readlane_b32 s51, v248, 16
	v_readlane_b32 s52, v248, 17
	v_readlane_b32 s53, v248, 18
	v_readlane_b32 s54, v248, 19
	v_readlane_b32 s55, v248, 20
	s_mov_b64 s[28:29], s[44:45]
	s_and_b32 s35, s36, 0xffffe31f
	s_bfe_u32 s26, s36, 0x30005
	s_lshl_b32 s26, s26, 10
	s_or_b32 s35, s35, s26
	s_bfe_u32 s26, s36, 0x3000a
	s_lshl_b32 s26, s26, 5
	s_or_b32 s35, s35, s26
	s_movk_i32 s26, 0x4000

; __device__ __forceinline__ int otid() { int t = threadIdx.x; asm volatile("" : "+v"(t)); return t; }
; __device__ __forceinline__ int obid() { int t = blockIdx.x; asm volatile("" : "+s"(t)); return t; }
; __device__ __forceinline__ void tr_store(const TDesc& d, int tid, const f32x4 (&v)[4], u16* lds) {
;   const int kg = tid >> 5, n4 = tid & 31;
; #pragma unroll
;   for (int e = 0; e < 4; ++e) {
;     u32x2 pk = {pk2(v[0][e], v[1][e]), pk2(v[2][e], v[3][e])};
;     *reinterpret_cast<u32x2*>(lds + (n4 * 4 + e) * 68 + kg * 4) = pk;
;   }
;   __syncthreads();
;   const int nn = tid >> 2, ks = tid & 3;
;   const u32x2* s = reinterpret_cast<const u32x2*>(lds + nn * 68 + ks * 16);
;   u32x2 a = s[0], b = s[1], c = s[2], e2 = s[3];
;   u32x4* o = reinterpret_cast<u32x4*>(d.dst + (long)(d.n0 + nn) * d.K + d.k0 + ks * 16);
;   if (d.nt) {
;     __builtin_nontemporal_store(u32x4{a[0], a[1], b[0], b[1]}, o);
;     __builtin_nontemporal_store(u32x4{c[0], c[1], e2[0], e2[1]}, o + 1);
;   } else {
;     o[0] = u32x4{a[0], a[1], b[0], b[1]};
;     o[1] = u32x4{c[0], c[1], e2[0], e2[1]};
;   }
; }
; __device__ __forceinline__ void phase_convert(const Params& p, u16* lds) {
;   const int tid = otid(), bid = obid();
;   if (bid == 0) {
;     if (tid < 256) WSP(int, WS_CTR)[tid] = 0;
;     for (int i = tid; i < XCD_BAR_WORDS; i += 512) WSP(unsigned, WS_BAR)[i] = 0u;
;   }
;   {
;     TDesc d0 = tr_locate(p, bid);
;     f32x4 v0[4];
;     tr_load(d0, tid, v0);
;     int buf = 0;
;     for (int tile = bid; d0.valid; tile += gridDim.x) {
;       TDesc d1 = tr_locate(p, tile + gridDim.x);
;       f32x4 v1[4];
;       tr_load(d1, tid, v1);
;       tr_store(d0, tid, v0, lds + buf * (128 * 68));
;       buf ^= 1;
;       d0 = d1;
; #pragma unroll
;       for (int r = 0; r < 4; ++r) v0[r] = v1[r];
;     }
.LBB0_319:
	s_or_b64 exec, exec, s[2:3]
	s_mul_i32 s2, s39, 0x4400
	s_add_i32 s2, s2, 64
	v_lshlrev_b32_e32 v45, 1, v38
	s_waitcnt vmcnt(0)
	v_cvt_pk_bf16_f32 v36,v2,v6
	v_cvt_pk_bf16_f32 v37,v10,v14
	v_add3_u32 v6, s2, v45, v42
	v_cvt_pk_bf16_f32 v2,v3,v7
	v_cvt_pk_bf16_f32 v3,v11,v15
	v_add_u32_e32 v10, s37, v43
	ds_write2_b64 v6, v[36:37], v[2:3] offset1:17
	v_cvt_pk_bf16_f32 v2,v4,v8
	v_cvt_pk_bf16_f32 v3,v12,v16
	v_cvt_pk_bf16_f32 v4,v5,v9
	v_cvt_pk_bf16_f32 v5,v13,v17
	ds_write2_b64 v6, v[2:3], v[4:5] offset0:34 offset1:51
	v_add3_u32 v6, s2, v44, v0
	v_ashrrev_i32_e32 v13, 31, v10
	v_mad_u64_u32 v[10:11], s[2:3], s27, v10, 0
	v_mov_b32_e32 v12, v11
	s_waitcnt lgkmcnt(0)
	s_barrier
	ds_read2_b64 v[2:5], v6 offset1:1
	ds_read2_b64 v[6:9], v6 offset0:2 offset1:3
	v_mad_u64_u32 v[12:13], s[2:3], s27, v13, v[12:13]
	v_mov_b32_e32 v11, v12
	v_lshl_add_u64 v[10:11], v[10:11], 1, s[10:11]
	s_ashr_i32 s27, s26, 31
	v_lshl_add_u64 v[10:11], s[26:27], 1, v[10:11]
	s_xor_b64 s[0:1], s[34:35], -1
	v_lshl_add_u64 v[10:11], v[10:11], 0, v[0:1]
	s_waitcnt lgkmcnt(1)
	flat_store_dwordx4 v[10:11], v[2:5]
	s_waitcnt lgkmcnt(0)
	flat_store_dwordx4 v[10:11], v[6:9] offset:16
	s_xor_b32 s39, s39, 1
	v_readlane_b32 s38, v247, 46
	s_nop 3
	s_add_i32 s38, s38, s94
	s_and_b64 vcc, exec, s[0:1]
	s_mov_b32 s37, s43
	s_mov_b32 s26, s44
	s_mov_b32 s27, s41
	s_mov_b64 s[10:11], s[28:29]
	v_mov_b32_e32 v2, v22
	v_mov_b32_e32 v3, v23
	v_mov_b32_e32 v4, v24
	v_mov_b32_e32 v5, v25
	v_mov_b32_e32 v6, v18
	v_mov_b32_e32 v7, v19
	v_mov_b32_e32 v8, v20
	v_mov_b32_e32 v9, v21
	v_mov_b32_e32 v10, v30
	v_mov_b32_e32 v11, v31
	v_mov_b32_e32 v12, v32
	v_mov_b32_e32 v13, v33
	v_mov_b32_e32 v14, v26
	v_mov_b32_e32 v15, v27
	v_mov_b32_e32 v16, v28
	v_mov_b32_e32 v17, v29
	s_cbranch_vccnz .LBB0_370
.LBB0_320:
	v_writelane_b32 v247, s38, 46
	s_cmpk_lt_u32 s38, 0x4000
	s_cbranch_scc0 .Lcvp_skip
	s_bfe_u32 s0, s38, 0x30005
	s_bfe_u32 s1, s38, 0x3000a
	s_and_b32 s38, s38, 0xffffe31f
	s_lshl_b32 s0, s0, 10
	s_lshl_b32 s1, s1, 5
	s_or_b32 s38, s38, s0
	s_or_b32 s38, s38, s1
.Lcvp_skip:
	s_mov_b32 s40, s38
	s_cmpk_gt_i32 s38, 0x1fff
	s_cselect_b64 s[0:1], -1, 0
	s_cmpk_lt_i32 s38, 0x2000
	s_cbranch_scc1 .LBB0_323
	s_add_i32 s43, s38, 0xffffe000
	s_movk_i32 s44, 0x80
	s_mov_b64 s[28:29], 0
	s_mov_b32 s42, 0
	s_mov_b32 s41, 0
	s_mov_b64 s[30:31], 0
	s_andn2_b64 vcc, exec, s[0:1]
	s_mov_b64 s[0:1], -1
	s_cbranch_vccz .LBB0_324
